# K=2816 GEMM: first K-loop iteration peeled with C=0 MFMAs (no accumulator zeroing) and epilogue parameter block loaded at unit set-up
# speedup vs baseline: 1.0085x; 1.0027x over previous
;     __host__ __device__ bool next(int i, Unit& u) const {
;         const long L = (long)i * G + c; if (L >= nwg) return false;
;         int wgid = (int)L; { const int q = nwg / NXCD, r = nwg % NXCD, xcd = wgid % NXCD, off = wgid / NXCD; wgid = (xcd < r ? xcd * (q + 1) : r * (q + 1) + (xcd - r) * q) + off; }
;         const int nig = WGM * nN, gid = wgid / nig, fm = gid * WGM, gsz = (nM - fm) < WGM ? (nM - fm) : WGM;
;         u.pm = fm + ((wgid % nig) % gsz); u.pn = (wgid % nig) / gsz; return true;
; template <class Epi, class Sched, bool ALIGN_EPI = false, bool SP2 = false>
; __device__ __forceinline__ void gemm_phase(PG8_LAS unsigned char* lds, const Gemm g, const Sched& S, const Epi& E, const int wave0) {
;     ...
;     for (;;) {
;         const bool has_next = S.next(ui + 1, nxt);
;         const char* nA = has_next ? (const char*)g.A + (size_t)nxt.pm * tstep : cA; const char* nB = has_next ? (const char*)g.Bt + (size_t)nxt.pn * tstep : cB;
.LBB0_1017:
	global_load_dwordx4 v[192:195], v215, s[40:41] offset:1024
	global_load_dwordx4 v[196:199], v215, s[40:41] offset:1064
	global_load_dwordx4 v[200:203], v215, s[40:41] offset:1048
	s_add_i32 s25, s25, 1
	s_mul_i32 s6, s25, s88
	s_mul_hi_u32 s7, s25, s72
	s_add_i32 s7, s7, s6
	s_mul_i32 s6, s25, s72
	s_add_u32 s6, s6, s21
	s_addc_u32 s7, s7, s26
	v_mov_b64_e32 v[0:1], s[42:43]
	v_cmp_ge_i64_e32 vcc, s[6:7], v[0:1]
	v_cmp_lt_i64_e64 s[8:9], s[6:7], v[0:1]
	s_cbranch_vccnz .LBB0_1019
	s_ashr_i32 s7, s6, 31
	s_lshr_b32 s7, s7, 29
	s_add_i32 s7, s6, s7
	s_ashr_i32 s18, s7, 3
	s_and_b32 s7, s7, -8
	s_sub_i32 s6, s6, s7
	s_lshr_b32 s7, s6, 31
	s_or_b32 s7, s27, s7
	s_mul_i32 s6, s7, s6
	s_add_i32 s6, s6, s18
	s_abs_i32 s18, s6
	s_mul_hi_u32 s19, s18, s52
	s_mul_i32 s44, s19, s24
	s_sub_i32 s18, s18, s44
	s_ashr_i32 s7, s6, 31
	s_add_i32 s44, s19, 1
	s_sub_i32 s45, s18, s24
	s_cmp_ge_u32 s18, s24
	s_cselect_b32 s19, s44, s19
	s_cselect_b32 s18, s45, s18
	s_add_i32 s44, s19, 1
	s_cmp_ge_u32 s18, s24
	s_cselect_b32 s18, s44, s19
	s_xor_b32 s18, s18, s7
	s_sub_i32 s7, s18, s7
	s_lshl_b32 s18, s7, 3
	s_sub_i32 s19, s35, s18
	s_min_i32 s19, s19, 8
	s_abs_i32 s44, s19
	v_cvt_f32_u32_e32 v0, s44
	s_sub_i32 s46, 0, s44
	s_mul_i32 s7, s7, s24
	s_sub_i32 s6, s6, s7
	v_rcp_iflag_f32_e32 v0, v0
	s_abs_i32 s45, s6
	s_xor_b32 s7, s6, s19
	s_ashr_i32 s7, s7, 31
	v_mul_f32_e32 v0, 0x4f7ffffe, v0
	v_cvt_u32_f32_e32 v0, v0
	s_nop 0
	v_readfirstlane_b32 s47, v0
	s_mul_i32 s46, s46, s47
	s_mul_hi_u32 s46, s47, s46
	s_add_i32 s47, s47, s46
	s_mul_hi_u32 s46, s45, s47
	s_mul_i32 s47, s46, s44
	s_sub_i32 s45, s45, s47
	s_add_i32 s47, s46, 1
	s_sub_i32 s50, s45, s44
	s_cmp_ge_u32 s45, s44
	s_cselect_b32 s46, s47, s46
	s_cselect_b32 s45, s50, s45
	s_add_i32 s47, s46, 1
	s_cmp_ge_u32 s45, s44
	s_cselect_b32 s44, s47, s46
	s_xor_b32 s44, s44, s7
	s_sub_i32 s53, s44, s7
	s_mul_i32 s7, s53, s19
	s_sub_i32 s6, s6, s7
	s_add_i32 s54, s6, s18

; #define PG8_STAGE(bufoff, gbase, voff) do { _Pragma("unroll") for (int _i = 0; _i < 2; ++_i) \
;         __builtin_amdgcn_global_load_lds((const unsigned*)((const char*)(gbase) + (voff)[_i]), (PG8_LAS unsigned*)(lds + (bufoff) + ldsw + _i * 8192), 16, 0, 0); } while (0)
; #define PG8_LDA(dst, b, h) do { _Pragma("unroll") for (int m = 0; m < 4; ++m) _Pragma("unroll") for (int k = 0; k < 2; ++k) dst[m][k] = *(const PG8_LAS bf16x8*)(lds + PG8_SA(b, h) + aoff + m * 2048 + k * 1024); } while (0)
; #define PG8_LDB(dst, b, h) do { _Pragma("unroll") for (int n = 0; n < 2; ++n) _Pragma("unroll") for (int k = 0; k < 2; ++k) dst[n][k] = *(const PG8_LAS bf16x8*)(lds + PG8_SB(b, h) + boff + n * 2048 + k * 1024); } while (0)
; #define PG8_MMA(ai, bj, At, Bt) do { __builtin_amdgcn_s_setprio(1); _Pragma("unroll") for (int m = 0; m < 4; ++m) _Pragma("unroll") for (int n = 0; n < 2; ++n) _Pragma("unroll") for (int k = 0; k < 2; ++k) \
;         acc[ai][bj][m][n] = __builtin_amdgcn_mfma_f32_16x16x32_bf16(Bt[n][k], At[m][k], acc[ai][bj][m][n], 0, 0, 0); __builtin_amdgcn_s_setprio(0); } while (0)
; #define PG8_WAIT_V(n) asm volatile("s_waitcnt vmcnt(" #n ")" ::: "memory")
; #define PG8_WAIT_L(n) asm volatile("s_waitcnt lgkmcnt(" #n ")" ::: "memory")
; #define PG8_BAR __builtin_amdgcn_s_barrier()
; #define PG8_SCHED __builtin_amdgcn_sched_barrier(0)
; template <class Epi, class Sched, bool ALIGN_EPI = false, bool SP2 = false>
; __device__ __forceinline__ void gemm_phase(PG8_LAS unsigned char* lds, const Gemm g, const Sched& S, const Epi& E, const int wave0) {
;     ...
;             PG8_LDB(B0, 0, 0); PG8_LDB(B1, 0, 1); PG8_SCHED; PG8_LDA(At, 0, 0); PG8_STAGE(PG8_SA(1, 1), a1 + hstep, voffA);
;             PG8_WAIT_V(8); PG8_WAIT_L(0); PG8_BAR; PG8_MMA(0, 0, At, B0); PG8_MMA(0, 1, At, B1); PG8_BAR; PG8_SCHED;
;             PG8_LDA(At, 0, 1); PG8_STAGE(PG8_SB(0, 0), b2, voffB); PG8_STAGE(PG8_SB(0, 1), b2 + hstep, voffB); PG8_STAGE(PG8_SA(0, 0), a2, voffA);
;             PG8_WAIT_V(8); PG8_WAIT_L(0); PG8_BAR; PG8_MMA(1, 0, At, B0); PG8_MMA(1, 1, At, B1); PG8_BAR; PG8_SCHED;
.LBB0_1023:
	s_add_u32 s57, s48, 0x100
	s_addc_u32 s58, s49, 0
	s_mov_b32 s59, -2
	s_waitcnt lgkmcnt(0)
	s_add_u32 s8, s10, 0x100
	s_addc_u32 s9, s11, 0
	s_add_i32 s18, 0, 0x10000
	s_cmp_eq_u32 s59, 40
	s_cselect_b32 s51, s45, s9
	s_cselect_b32 s50, s44, s8
	s_cselect_b32 s49, s47, s58
	s_cselect_b32 s48, s46, s57
	s_add_i32 s19, 0, 0x14000
	v_add_u32_e32 v140, s18, v247
	v_add_u32_e32 v156, s19, v247
	ds_read_b128 v[64:67], v140
	ds_read_b128 v[68:71], v140 offset:1024
	ds_read_b128 v[136:139], v140 offset:2048
	ds_read_b128 v[140:143], v140 offset:3072
	ds_read_b128 v[144:147], v156
	ds_read_b128 v[148:151], v156 offset:1024
	ds_read_b128 v[152:155], v156 offset:2048
	ds_read_b128 v[156:159], v156 offset:3072
	s_add_i32 m0, s33, 0xc000
	ds_read_b128 v[160:163], v245
	ds_read_b128 v[164:167], v245 offset:1024
	ds_read_b128 v[168:171], v245 offset:2048
	ds_read_b128 v[172:175], v245 offset:3072
	ds_read_b128 v[176:179], v245 offset:4096
	ds_read_b128 v[180:183], v245 offset:5120
	ds_read_b128 v[184:187], v245 offset:6144
	ds_read_b128 v[188:191], v245 offset:7168
	global_load_lds_dwordx4 v224, s[10:11]
	s_add_i32 m0, s33, 0xe000
	s_nop 0
	global_load_lds_dwordx4 v226, s[10:11]
	s_waitcnt vmcnt(8)
	s_waitcnt lgkmcnt(0)
	s_barrier
	s_setprio 1
	v_mfma_f32_16x16x32_bf16 v[132:135], v[64:67], v[160:163], 0
	v_mfma_f32_16x16x32_bf16 v[128:131], v[136:139], v[160:163], 0
	v_mfma_f32_16x16x32_bf16 v[116:119], v[64:67], v[168:171], 0
	v_mfma_f32_16x16x32_bf16 v[108:111], v[136:139], v[168:171], 0
	v_mfma_f32_16x16x32_bf16 v[100:103], v[64:67], v[176:179], 0
	v_mfma_f32_16x16x32_bf16 v[92:95], v[136:139], v[176:179], 0
	v_mfma_f32_16x16x32_bf16 v[84:87], v[64:67], v[184:187], 0
	v_mfma_f32_16x16x32_bf16 v[76:79], v[136:139], v[184:187], 0
	v_mfma_f32_16x16x32_bf16 v[132:135], v[68:71], v[164:167], v[132:135]
	v_mfma_f32_16x16x32_bf16 v[128:131], v[140:143], v[164:167], v[128:131]
	v_mfma_f32_16x16x32_bf16 v[116:119], v[68:71], v[172:175], v[116:119]
	v_mfma_f32_16x16x32_bf16 v[108:111], v[140:143], v[172:175], v[108:111]
	v_mfma_f32_16x16x32_bf16 v[100:103], v[68:71], v[180:183], v[100:103]
	v_mfma_f32_16x16x32_bf16 v[92:95], v[140:143], v[180:183], v[92:95]
	v_mfma_f32_16x16x32_bf16 v[84:87], v[68:71], v[188:191], v[84:87]
	v_mfma_f32_16x16x32_bf16 v[76:79], v[140:143], v[188:191], v[76:79]
	v_mfma_f32_16x16x32_bf16 v[124:127], v[144:147], v[160:163], 0
	v_mfma_f32_16x16x32_bf16 v[120:123], v[152:155], v[160:163], 0
	v_mfma_f32_16x16x32_bf16 v[112:115], v[144:147], v[168:171], 0
	v_mfma_f32_16x16x32_bf16 v[104:107], v[152:155], v[168:171], 0
	v_mfma_f32_16x16x32_bf16 v[96:99], v[144:147], v[176:179], 0
	v_mfma_f32_16x16x32_bf16 v[88:91], v[152:155], v[176:179], 0
	v_mfma_f32_16x16x32_bf16 v[80:83], v[144:147], v[184:187], 0
	v_mfma_f32_16x16x32_bf16 v[72:75], v[152:155], v[184:187], 0
	v_mfma_f32_16x16x32_bf16 v[124:127], v[148:151], v[164:167], v[124:127]
	v_mfma_f32_16x16x32_bf16 v[120:123], v[156:159], v[164:167], v[120:123]
	v_mfma_f32_16x16x32_bf16 v[112:115], v[148:151], v[172:175], v[112:115]
	v_mfma_f32_16x16x32_bf16 v[104:107], v[156:159], v[172:175], v[104:107]
	v_mfma_f32_16x16x32_bf16 v[96:99], v[148:151], v[180:183], v[96:99]
	v_mfma_f32_16x16x32_bf16 v[88:91], v[156:159], v[180:183], v[88:91]
	v_mfma_f32_16x16x32_bf16 v[80:83], v[148:151], v[188:191], v[80:83]
	v_mfma_f32_16x16x32_bf16 v[72:75], v[156:159], v[188:191], v[72:75]
	s_setprio 0
	s_barrier
	s_add_i32 s10, s18, s95
	s_mov_b32 m0, s10
	ds_read_b128 v[160:163], v245 offset:16384
	ds_read_b128 v[164:167], v245 offset:17408
	ds_read_b128 v[168:171], v245 offset:18432
	ds_read_b128 v[172:175], v245 offset:19456
	ds_read_b128 v[176:179], v245 offset:20480
	ds_read_b128 v[180:183], v245 offset:21504
	ds_read_b128 v[184:187], v245 offset:22528
	ds_read_b128 v[188:191], v245 offset:23552
	global_load_lds_dwordx4 v218, s[48:49]
	s_add_i32 m0, s10, 0x2000
	s_add_u32 s10, s48, 0xb0000
	s_addc_u32 s11, s49, 0
	s_add_i32 s18, s19, s95
	global_load_lds_dwordx4 v222, s[48:49]
	s_mov_b32 m0, s18
	s_nop 0
	global_load_lds_dwordx4 v218, s[10:11]
	s_add_i32 m0, s18, 0x2000
	s_nop 0
	global_load_lds_dwordx4 v222, s[10:11]
	s_mov_b32 m0, s33
	s_nop 0
	global_load_lds_dwordx4 v216, s[50:51]
	s_mov_b32 m0, s82
	s_nop 0
	global_load_lds_dwordx4 v220, s[50:51]
	s_waitcnt vmcnt(8)
	s_waitcnt lgkmcnt(0)
	s_barrier
	s_setprio 1
	v_mfma_f32_16x16x32_bf16 v[60:63], v[64:67], v[160:163], 0
	v_mfma_f32_16x16x32_bf16 v[52:55], v[136:139], v[160:163], 0
	v_mfma_f32_16x16x32_bf16 v[44:47], v[64:67], v[168:171], 0
	v_mfma_f32_16x16x32_bf16 v[36:39], v[136:139], v[168:171], 0
	v_mfma_f32_16x16x32_bf16 v[28:31], v[64:67], v[176:179], 0
	v_mfma_f32_16x16x32_bf16 v[20:23], v[136:139], v[176:179], 0
	v_mfma_f32_16x16x32_bf16 v[12:15], v[64:67], v[184:187], 0
	v_mfma_f32_16x16x32_bf16 v[4:7], v[136:139], v[184:187], 0
	v_mfma_f32_16x16x32_bf16 v[60:63], v[68:71], v[164:167], v[60:63]
	v_mfma_f32_16x16x32_bf16 v[52:55], v[140:143], v[164:167], v[52:55]
	v_mfma_f32_16x16x32_bf16 v[44:47], v[68:71], v[172:175], v[44:47]
	v_mfma_f32_16x16x32_bf16 v[36:39], v[140:143], v[172:175], v[36:39]
	v_mfma_f32_16x16x32_bf16 v[28:31], v[68:71], v[180:183], v[28:31]
	v_mfma_f32_16x16x32_bf16 v[20:23], v[140:143], v[180:183], v[20:23]
	v_mfma_f32_16x16x32_bf16 v[12:15], v[68:71], v[188:191], v[12:15]
	v_mfma_f32_16x16x32_bf16 v[4:7], v[140:143], v[188:191], v[4:7]
	v_mfma_f32_16x16x32_bf16 v[56:59], v[144:147], v[160:163], 0
	v_mfma_f32_16x16x32_bf16 v[48:51], v[152:155], v[160:163], 0
	v_mfma_f32_16x16x32_bf16 v[40:43], v[144:147], v[168:171], 0
	v_mfma_f32_16x16x32_bf16 v[32:35], v[152:155], v[168:171], 0
	v_mfma_f32_16x16x32_bf16 v[24:27], v[144:147], v[176:179], 0
	v_mfma_f32_16x16x32_bf16 v[16:19], v[152:155], v[176:179], 0
	v_mfma_f32_16x16x32_bf16 v[8:11], v[144:147], v[184:187], 0
	v_mfma_f32_16x16x32_bf16 v[0:3], v[152:155], v[184:187], 0
	v_mfma_f32_16x16x32_bf16 v[56:59], v[148:151], v[164:167], v[56:59]
	v_mfma_f32_16x16x32_bf16 v[48:51], v[156:159], v[164:167], v[48:51]
	v_mfma_f32_16x16x32_bf16 v[40:43], v[148:151], v[172:175], v[40:43]
	v_mfma_f32_16x16x32_bf16 v[32:35], v[156:159], v[172:175], v[32:35]
	v_mfma_f32_16x16x32_bf16 v[24:27], v[148:151], v[180:183], v[24:27]
	v_mfma_f32_16x16x32_bf16 v[16:19], v[156:159], v[180:183], v[16:19]
	v_mfma_f32_16x16x32_bf16 v[8:11], v[148:151], v[188:191], v[8:11]
	v_mfma_f32_16x16x32_bf16 v[0:3], v[156:159], v[188:191], v[0:3]
	s_setprio 0
	s_barrier
; #define PG8_STAGE(bufoff, gbase, voff) do { _Pragma("unroll") for (int _i = 0; _i < 2; ++_i) \
;         __builtin_amdgcn_global_load_lds((const unsigned*)((const char*)(gbase) + (voff)[_i]), (PG8_LAS unsigned*)(lds + (bufoff) + ldsw + _i * 8192), 16, 0, 0); } while (0)
; #define PG8_LDA(dst, b, h) do { _Pragma("unroll") for (int m = 0; m < 4; ++m) _Pragma("unroll") for (int k = 0; k < 2; ++k) dst[m][k] = *(const PG8_LAS bf16x8*)(lds + PG8_SA(b, h) + aoff + m * 2048 + k * 1024); } while (0)
; #define PG8_LDB(dst, b, h) do { _Pragma("unroll") for (int n = 0; n < 2; ++n) _Pragma("unroll") for (int k = 0; k < 2; ++k) dst[n][k] = *(const PG8_LAS bf16x8*)(lds + PG8_SB(b, h) + boff + n * 2048 + k * 1024); } while (0)
; #define PG8_MMA(ai, bj, At, Bt) do { __builtin_amdgcn_s_setprio(1); _Pragma("unroll") for (int m = 0; m < 4; ++m) _Pragma("unroll") for (int n = 0; n < 2; ++n) _Pragma("unroll") for (int k = 0; k < 2; ++k) \
;         acc[ai][bj][m][n] = __builtin_amdgcn_mfma_f32_16x16x32_bf16(Bt[n][k], At[m][k], acc[ai][bj][m][n], 0, 0, 0); __builtin_amdgcn_s_setprio(0); } while (0)
; #define PG8_WAIT_V(n) asm volatile("s_waitcnt vmcnt(" #n ")" ::: "memory")
; #define PG8_WAIT_L(n) asm volatile("s_waitcnt lgkmcnt(" #n ")" ::: "memory")
; #define PG8_BAR __builtin_amdgcn_s_barrier()
; #define PG8_SCHED __builtin_amdgcn_sched_barrier(0)
; template <class Epi, class Sched, bool ALIGN_EPI = false, bool SP2 = false>
; __device__ __forceinline__ void gemm_phase(PG8_LAS unsigned char* lds, const Gemm g, const Sched& S, const Epi& E, const int wave0) {
;     ...
;             PG8_LDB(B0, 1, 0); PG8_LDB(B1, 1, 1); PG8_SCHED; PG8_LDA(At, 1, 0); PG8_STAGE(PG8_SA(0, 1), a2 + hstep, voffA);
;             PG8_WAIT_V(8); PG8_WAIT_L(0); PG8_BAR; PG8_MMA(0, 0, At, B0); PG8_MMA(0, 1, At, B1); PG8_BAR; PG8_SCHED;
;             PG8_LDA(At, 1, 1); PG8_STAGE(PG8_SB(1, 0), b3, voffB); PG8_STAGE(PG8_SB(1, 1), b3 + hstep, voffB); PG8_STAGE(PG8_SA(1, 0), a3, voffA);
;             PG8_WAIT_V(8); PG8_WAIT_L(0); PG8_BAR; PG8_MMA(1, 0, At, B0); PG8_MMA(1, 1, At, B1); PG8_BAR; PG8_SCHED;
	s_add_i32 s18, 0, 0x18000
	s_add_i32 s19, 0, 0x1c000
	v_add_u32_e32 v140, s18, v247
	v_add_u32_e32 v156, s19, v247
	ds_read_b128 v[64:67], v140
	ds_read_b128 v[68:71], v140 offset:1024
	ds_read_b128 v[136:139], v140 offset:2048
	ds_read_b128 v[140:143], v140 offset:3072
	ds_read_b128 v[144:147], v156
	ds_read_b128 v[148:151], v156 offset:1024
	ds_read_b128 v[152:155], v156 offset:2048
	ds_read_b128 v[156:159], v156 offset:3072
	s_add_u32 s10, s50, 0xb0000
	s_addc_u32 s11, s51, 0
	s_mov_b32 m0, s16
	ds_read_b128 v[160:163], v245 offset:32768
	ds_read_b128 v[164:167], v245 offset:33792
	ds_read_b128 v[168:171], v245 offset:34816
	ds_read_b128 v[172:175], v245 offset:35840
	ds_read_b128 v[176:179], v245 offset:36864
	ds_read_b128 v[180:183], v245 offset:37888
	ds_read_b128 v[184:187], v245 offset:38912
	ds_read_b128 v[188:191], v245 offset:39936
	global_load_lds_dwordx4 v216, s[10:11]
	s_mov_b32 m0, s83
	s_nop 0
	global_load_lds_dwordx4 v220, s[10:11]
	s_waitcnt vmcnt(8)
	s_waitcnt lgkmcnt(0)
	s_barrier
	s_setprio 1
	v_mfma_f32_16x16x32_bf16 v[132:135], v[64:67], v[160:163], v[132:135]
	v_mfma_f32_16x16x32_bf16 v[128:131], v[136:139], v[160:163], v[128:131]
	v_mfma_f32_16x16x32_bf16 v[116:119], v[64:67], v[168:171], v[116:119]
	v_mfma_f32_16x16x32_bf16 v[108:111], v[136:139], v[168:171], v[108:111]
	v_mfma_f32_16x16x32_bf16 v[100:103], v[64:67], v[176:179], v[100:103]
	v_mfma_f32_16x16x32_bf16 v[92:95], v[136:139], v[176:179], v[92:95]
	v_mfma_f32_16x16x32_bf16 v[84:87], v[64:67], v[184:187], v[84:87]
	v_mfma_f32_16x16x32_bf16 v[76:79], v[136:139], v[184:187], v[76:79]
	v_mfma_f32_16x16x32_bf16 v[132:135], v[68:71], v[164:167], v[132:135]
	v_mfma_f32_16x16x32_bf16 v[128:131], v[140:143], v[164:167], v[128:131]
	v_mfma_f32_16x16x32_bf16 v[116:119], v[68:71], v[172:175], v[116:119]
	v_mfma_f32_16x16x32_bf16 v[108:111], v[140:143], v[172:175], v[108:111]
	v_mfma_f32_16x16x32_bf16 v[100:103], v[68:71], v[180:183], v[100:103]
	v_mfma_f32_16x16x32_bf16 v[92:95], v[140:143], v[180:183], v[92:95]
	v_mfma_f32_16x16x32_bf16 v[84:87], v[68:71], v[188:191], v[84:87]
	v_mfma_f32_16x16x32_bf16 v[76:79], v[140:143], v[188:191], v[76:79]
	v_mfma_f32_16x16x32_bf16 v[124:127], v[144:147], v[160:163], v[124:127]
	v_mfma_f32_16x16x32_bf16 v[120:123], v[152:155], v[160:163], v[120:123]
	v_mfma_f32_16x16x32_bf16 v[112:115], v[144:147], v[168:171], v[112:115]
	v_mfma_f32_16x16x32_bf16 v[104:107], v[152:155], v[168:171], v[104:107]
	v_mfma_f32_16x16x32_bf16 v[96:99], v[144:147], v[176:179], v[96:99]
	v_mfma_f32_16x16x32_bf16 v[88:91], v[152:155], v[176:179], v[88:91]
	v_mfma_f32_16x16x32_bf16 v[80:83], v[144:147], v[184:187], v[80:83]
	v_mfma_f32_16x16x32_bf16 v[72:75], v[152:155], v[184:187], v[72:75]
	v_mfma_f32_16x16x32_bf16 v[124:127], v[148:151], v[164:167], v[124:127]
	v_mfma_f32_16x16x32_bf16 v[120:123], v[156:159], v[164:167], v[120:123]
	v_mfma_f32_16x16x32_bf16 v[112:115], v[148:151], v[172:175], v[112:115]
	v_mfma_f32_16x16x32_bf16 v[104:107], v[156:159], v[172:175], v[104:107]
	v_mfma_f32_16x16x32_bf16 v[96:99], v[148:151], v[180:183], v[96:99]
	v_mfma_f32_16x16x32_bf16 v[88:91], v[156:159], v[180:183], v[88:91]
	v_mfma_f32_16x16x32_bf16 v[80:83], v[148:151], v[188:191], v[80:83]
	v_mfma_f32_16x16x32_bf16 v[72:75], v[156:159], v[188:191], v[72:75]
	s_setprio 0
	s_barrier
	s_add_i32 s10, s18, s95
	s_add_i32 m0, s10, 0xffffff80
	ds_read_b128 v[160:163], v245 offset:49152
	ds_read_b128 v[164:167], v245 offset:50176
	ds_read_b128 v[168:171], v245 offset:51200
	ds_read_b128 v[172:175], v245 offset:52224
	ds_read_b128 v[176:179], v245 offset:53248
	ds_read_b128 v[180:183], v245 offset:54272
	ds_read_b128 v[184:187], v245 offset:55296
	ds_read_b128 v[188:191], v245 offset:56320
	global_load_lds_dwordx4 v218, s[48:49] offset:128
	s_add_i32 m0, s10, 0x1f80
	s_add_u32 s10, s48, 0xb0080
	s_addc_u32 s11, s49, 0
	s_add_i32 s18, s19, s95
	global_load_lds_dwordx4 v222, s[48:49] offset:128
	s_mov_b32 m0, s18
	s_nop 0
	global_load_lds_dwordx4 v218, s[10:11]
	s_add_i32 m0, s18, 0x2000
	s_nop 0
	global_load_lds_dwordx4 v222, s[10:11]
	s_add_i32 m0, s17, 0xffffff80
	s_nop 0
	global_load_lds_dwordx4 v216, s[50:51] offset:128
	s_add_i32 m0, s23, 0xffffff80
	s_nop 0
	global_load_lds_dwordx4 v220, s[50:51] offset:128
	s_waitcnt vmcnt(8)
	s_waitcnt lgkmcnt(0)
	s_barrier
	s_setprio 1
	v_mfma_f32_16x16x32_bf16 v[60:63], v[64:67], v[160:163], v[60:63]
	v_mfma_f32_16x16x32_bf16 v[52:55], v[136:139], v[160:163], v[52:55]
	v_mfma_f32_16x16x32_bf16 v[44:47], v[64:67], v[168:171], v[44:47]
	v_mfma_f32_16x16x32_bf16 v[36:39], v[136:139], v[168:171], v[36:39]
	v_mfma_f32_16x16x32_bf16 v[28:31], v[64:67], v[176:179], v[28:31]
	v_mfma_f32_16x16x32_bf16 v[20:23], v[136:139], v[176:179], v[20:23]
	v_mfma_f32_16x16x32_bf16 v[12:15], v[64:67], v[184:187], v[12:15]
	v_mfma_f32_16x16x32_bf16 v[4:7], v[136:139], v[184:187], v[4:7]
	v_mfma_f32_16x16x32_bf16 v[60:63], v[68:71], v[164:167], v[60:63]
	v_mfma_f32_16x16x32_bf16 v[52:55], v[140:143], v[164:167], v[52:55]
	v_mfma_f32_16x16x32_bf16 v[44:47], v[68:71], v[172:175], v[44:47]
	v_mfma_f32_16x16x32_bf16 v[36:39], v[140:143], v[172:175], v[36:39]
	v_mfma_f32_16x16x32_bf16 v[28:31], v[68:71], v[180:183], v[28:31]
	v_mfma_f32_16x16x32_bf16 v[20:23], v[140:143], v[180:183], v[20:23]
	v_mfma_f32_16x16x32_bf16 v[12:15], v[68:71], v[188:191], v[12:15]
	v_mfma_f32_16x16x32_bf16 v[4:7], v[140:143], v[188:191], v[4:7]
	v_mfma_f32_16x16x32_bf16 v[56:59], v[144:147], v[160:163], v[56:59]
	v_mfma_f32_16x16x32_bf16 v[48:51], v[152:155], v[160:163], v[48:51]
	v_mfma_f32_16x16x32_bf16 v[40:43], v[144:147], v[168:171], v[40:43]
	v_mfma_f32_16x16x32_bf16 v[32:35], v[152:155], v[168:171], v[32:35]
	v_mfma_f32_16x16x32_bf16 v[24:27], v[144:147], v[176:179], v[24:27]
	v_mfma_f32_16x16x32_bf16 v[16:19], v[152:155], v[176:179], v[16:19]
	v_mfma_f32_16x16x32_bf16 v[8:11], v[144:147], v[184:187], v[8:11]
	v_mfma_f32_16x16x32_bf16 v[0:3], v[152:155], v[184:187], v[0:3]
	v_mfma_f32_16x16x32_bf16 v[56:59], v[148:151], v[164:167], v[56:59]
	v_mfma_f32_16x16x32_bf16 v[48:51], v[156:159], v[164:167], v[48:51]
	v_mfma_f32_16x16x32_bf16 v[40:43], v[148:151], v[172:175], v[40:43]
	v_mfma_f32_16x16x32_bf16 v[32:35], v[156:159], v[172:175], v[32:35]
	v_mfma_f32_16x16x32_bf16 v[24:27], v[148:151], v[180:183], v[24:27]
	v_mfma_f32_16x16x32_bf16 v[16:19], v[156:159], v[180:183], v[16:19]
	v_mfma_f32_16x16x32_bf16 v[8:11], v[148:151], v[188:191], v[8:11]
	v_mfma_f32_16x16x32_bf16 v[0:3], v[156:159], v[188:191], v[0:3]
	s_setprio 0
	s_barrier
	s_add_i32 s59, s59, 2
	s_add_u32 s57, s57, 0x100
	s_addc_u32 s58, s58, 0
	s_cmp_gt_u32 s59, 41
	s_mov_b64 s[10:11], s[8:9]

; __device__ __forceinline__ unsigned cvtpk(float lo, float hi) { f32x2 v = {lo, hi}; bf16x2_t b = __builtin_convertvector(v, bf16x2_t); return __builtin_bit_cast(unsigned, b); }
;     __device__ __forceinline__ void operator()(const pg8::f32x4 (&acc)[2][2][4][2], const pg8::Unit& u, int wr, int wc, int fr, int fq) const {
;         const int kind = p->kind, ldc = p->ldc, ncols = p->ncols, flags = p->flags; const float coef = p->coef;
;         const float* fin = (const float*)p->fin; float* fout = (float*)p->fout; bf16_t* o0 = (bf16_t*)p->o0; bf16_t* o1 = (bf16_t*)p->o1; const float* aux = (const float*)p->aux;
;         const int rowb = u.pm * 256 + wr * 64 + fr;
;         const int colb = u.pn * 256 + wc * 32 + (PERM ? 8 : 4) * fq;
;         constexpr int NS = PERM ? 4 : 16;
;         if (kind == EK_ACT) {
;     ...
;         } else if (kind == EK_BF16 && PERM) {
; #pragma unroll
;             for (int bj = 0; bj < 2; ++bj) {
;                 const int c = colb + 128 * bj;
;                 if (c < ncols) {
; #pragma unroll
;                     for (int ai = 0; ai < 2; ++ai)
; #pragma unroll
;                         for (int m = 0; m < 4; ++m) {
;                             pg8::f32x4 v0 = acc[ai][bj][m][0], v1 = acc[ai][bj][m][1];
;                             if (flags & 4) { const float rs = __builtin_amdgcn_rsqf(fin[rowb + 128 * ai + 16 * m] * (1.0f / DM) + EPS); v0 = v0 * rs; v1 = v1 * rs; }
;                             *(u32x4*)(o0 + (size_t)(rowb + 128 * ai + 16 * m) * ldc + c) = (u32x4){cvtpk(v0[0], v0[1]), cvtpk(v0[2], v0[3]), cvtpk(v1[0], v1[1]), cvtpk(v1[2], v1[3])};
.LBB0_1027:
	v_mov_b32_e32 v64, v192
	v_mov_b32_e32 v65, v193
	v_mov_b32_e32 v66, v194
	v_mov_b32_e32 v67, v195
	v_mov_b32_e32 v68, v196
	v_mov_b32_e32 v69, v197
	v_mov_b32_e32 v70, v198
	v_mov_b32_e32 v71, v199
	v_mov_b32_e32 v136, v200
	v_mov_b32_e32 v137, v201
	v_mov_b32_e32 v138, v202
	v_mov_b32_e32 v139, v203
	v_lshl_add_u32 v228, s56, 8, v252
	s_mov_b64 s[8:9], -1
	v_readfirstlane_b32 s50, v192
	s_cmp_lt_i32 s50, 1
	s_cbranch_scc1 .LBB0_1119
	v_lshl_or_b32 v230, s55, 8, v248
	s_cmp_lt_i32 s50, 2
	s_cbranch_scc1 .LBB0_1068
	s_cmp_eq_u32 s50, 2
	s_cbranch_scc0 .LBB0_1067
	v_and_b32_e32 v64, 4, v67
	v_cmp_ne_u32_e64 s[8:9], 0, v64
	v_cmp_lt_i32_e32 vcc, v230, v66
	s_nop 0
	v_cndmask_b32_e64 v64, 0, 1, s[8:9]
	v_cmp_ne_u32_e64 s[8:9], 1, v64
	s_and_saveexec_b64 s[10:11], vcc
	s_cbranch_execz .LBB0_1048
	v_ashrrev_i32_e32 v229, 31, v228
	v_mov_b64_e32 v[142:143], v[134:135]
	v_mov_b64_e32 v[146:147], v[130:131]
	s_and_b64 vcc, exec, s[8:9]
	v_lshl_add_u64 v[150:151], v[228:229], 2, v[136:137]
	v_mov_b64_e32 v[140:141], v[132:133]
	v_mov_b64_e32 v[144:145], v[128:129]
	s_cbranch_vccnz .LBB0_1033
	global_load_dword v64, v[150:151], off
	s_waitcnt vmcnt(0)
	v_fmamk_f32 v64, v64, 0x3a800000, v244
	v_rsq_f32_e32 v64, v64
	s_nop 0
	v_pk_mul_f32 v[142:143], v[134:135], v[64:65] op_sel_hi:[1,0]
	v_pk_mul_f32 v[140:141], v[132:133], v[64:65] op_sel_hi:[1,0]
	v_pk_mul_f32 v[146:147], v[130:131], v[64:65] op_sel_hi:[1,0]
	v_pk_mul_f32 v[144:145], v[128:129], v[64:65] op_sel_hi:[1,0]
